# select_row: chunks 0/1 key conversion as ashr+bitop3, chunk-1 index masking only when t < 511
# baseline (speedup 1.0000x reference)
; DI void select_row(const float* SC, unsigned* dmask, int b, int t, int lane) {
;     ...
;     for (int k = 0; k < 8; ++k) {
;         if (k < nch) {
;             const f32x4 v = *(const f32x4*)(srow + 256 * k);
; #pragma unroll
;             for (int e = 0; e < 4; ++e) { const unsigned bits = __builtin_bit_cast(unsigned, v[e] + 0.0f); const unsigned key = ((int)bits < 0) ? ~bits : (bits | 0x80000000u);
;                 u[k][e] = (256 * k + 4 * lane + e <= t) ? key : 0u; }
;         } else { u[k][0] = 0u; u[k][1] = 0u; u[k][2] = 0u; u[k][3] = 0u; }
;     }
.Lsel_cv_7:
.LBB0_549:
	s_waitcnt vmcnt(0)
	v_pk_add_f32 v[6:7], v[6:7], 0 op_sel_hi:[1,0]
	v_pk_add_f32 v[8:9], v[8:9], 0 op_sel_hi:[1,0]
	v_pk_add_f32 v[2:3], v[2:3], 0 op_sel_hi:[1,0]
	v_pk_add_f32 v[4:5], v[4:5], 0 op_sel_hi:[1,0]
	v_ashrrev_i32_e32 v146, 31, v6
	v_ashrrev_i32_e32 v147, 31, v7
	v_ashrrev_i32_e32 v148, 31, v8
	v_ashrrev_i32_e32 v149, 31, v9
	v_bitop3_b32 v11, v6, v146, s99 bitop3:0x1e
	v_bitop3_b32 v10, v7, v147, s99 bitop3:0x1e
	v_bitop3_b32 v121, v8, v148, s99 bitop3:0x1e
	v_bitop3_b32 v9, v9, v149, s99 bitop3:0x1e
	v_ashrrev_i32_e32 v146, 31, v2
	v_ashrrev_i32_e32 v147, 31, v3
	v_ashrrev_i32_e32 v148, 31, v4
	v_ashrrev_i32_e32 v149, 31, v5
	v_bitop3_b32 v7, v2, v146, s99 bitop3:0x1e
	v_bitop3_b32 v6, v3, v147, s99 bitop3:0x1e
	v_bitop3_b32 v8, v4, v148, s99 bitop3:0x1e
	v_bitop3_b32 v5, v5, v149, s99 bitop3:0x1e
	s_cmpk_gt_u32 s65, 0x1fe
	s_cbranch_scc1 .Lsel_cv_1
	v_cmp_ge_u32_e32 vcc, s65, v90
	s_nop 1
	v_cndmask_b32_e32 v7, 0, v7, vcc
	v_cmp_ge_u32_e32 vcc, s65, v83
	s_nop 1
	v_cndmask_b32_e32 v6, 0, v6, vcc
	v_cmp_ge_u32_e32 vcc, s65, v92
	s_nop 1
	v_cndmask_b32_e32 v8, 0, v8, vcc
	v_cmp_ge_u32_e32 vcc, s65, v85
	s_nop 1
	v_cndmask_b32_e32 v5, 0, v5, vcc
.Lsel_cv_1:
	v_mov_b32_e32 v1, v43
	v_cmp_le_u32_e32 vcc, s62, v11
	v_addc_co_u32_e32 v1, vcc, 0, v1, vcc
	v_cndmask_b32_e64 v2, 0, 1, s[10:11]
	v_cmp_le_u32_e32 vcc, s62, v10
	v_addc_co_u32_e32 v1, vcc, 0, v1, vcc
	v_cmp_ne_u32_e64 s[82:83], 1, v2
	v_cmp_le_u32_e32 vcc, s62, v121
	v_addc_co_u32_e32 v1, vcc, 0, v1, vcc
	v_cmp_le_u32_e32 vcc, s62, v9
	v_addc_co_u32_e32 v1, vcc, 0, v1, vcc
	v_cmp_le_u32_e32 vcc, s62, v7
	v_addc_co_u32_e32 v1, vcc, 0, v1, vcc
	v_cmp_le_u32_e32 vcc, s62, v6
	v_addc_co_u32_e32 v1, vcc, 0, v1, vcc
	v_cmp_le_u32_e32 vcc, s62, v8
	v_addc_co_u32_e32 v1, vcc, 0, v1, vcc
	v_cmp_le_u32_e32 vcc, s62, v5
	v_addc_co_u32_e32 v1, vcc, 0, v1, vcc
	s_andn2_b64 vcc, exec, s[10:11]
	s_cbranch_vccnz .LBB0_566
	v_cmp_le_u32_e32 vcc, s62, v33
	v_addc_co_u32_e32 v1, vcc, 0, v1, vcc
	v_cmp_le_u32_e32 vcc, s62, v41
	v_addc_co_u32_e32 v1, vcc, 0, v1, vcc
	v_cmp_le_u32_e32 vcc, s62, v32
	v_addc_co_u32_e32 v1, vcc, 0, v1, vcc
	v_cmp_le_u32_e32 vcc, s62, v42
	v_addc_co_u32_e32 v1, vcc, 0, v1, vcc
	v_cmp_le_u32_e32 vcc, s62, v29
	v_addc_co_u32_e32 v1, vcc, 0, v1, vcc
	v_cmp_le_u32_e32 vcc, s62, v30
	v_addc_co_u32_e32 v1, vcc, 0, v1, vcc
	v_cmp_le_u32_e32 vcc, s62, v28
	v_addc_co_u32_e32 v1, vcc, 0, v1, vcc
	v_cmp_le_u32_e32 vcc, s62, v31
	v_addc_co_u32_e32 v1, vcc, 0, v1, vcc
	v_cndmask_b32_e64 v2, 0, 1, s[76:77]
	v_cmp_ne_u32_e64 s[78:79], 1, v2
	s_andn2_b64 vcc, exec, s[76:77]
	s_cbranch_vccz .LBB0_567
